# v021 + indexer: exact 0.125 scale folded into staged head weights (32 fewer v_mul per two heads)
# speedup vs baseline: 1.0011x; 1.0011x over previous
; #define GAS __attribute__((address_space(1)))
; #define LAS __attribute__((address_space(3)))
; __device__ __forceinline__ void idx_unit(Frame& F, int samp, int b, int qb, int part = -1) {
;     ...
;     const int row0 = samp ? NP + b * TS + 32 * qb : b * TP + 32 * qb;
;     const int nadm = samp ? SALL : ((qb >> 1) + 1) * 64, nst = nadm / 32;
;     LAS unsigned char* lds = F.lds; LAS float* wiT = (LAS float*)(lds + 32 * QISTR);
;     const bf16* QI = (const bf16*)(F.ws + WS_QI); const bf16* KI = (const bf16*)(F.ws + WS_KI); const float* WI = (const float*)(F.ws + WS_WI);
;     float* SC = (float*)(F.ws + WS_SC); const int scld = samp ? SALL : 2048; float* sc0 = samp ? SC + SC_S_OFF + (size_t)(row0 - NP) * SALL : SC + (size_t)row0 * 2048;
; #pragma unroll
;     for (int i = 0; i < 8; ++i) { const int p = tid + 512 * i, r = p >> 7, c = p & 127; *(LAS v4u*)(lds + r * QISTR + c * 16) = *(const GAS v4u*)(QI + (size_t)(row0 + r) * 1024 + c * 8); }
;     wiT[(tid & 15) * 32 + (tid >> 4)] = WI[(size_t)(row0 + (tid >> 4)) * 16 + (tid & 15)];
;     __syncthreads();
;     const int st0 = part < 0 ? 0 : (part * nst) >> 2, st1 = part < 0 ? nst : ((part + 1) * nst) >> 2;
;     for (int U = F.bid; U < (F.G == 256 ? 256 : 320); U += F.G) {
;         if (U < 256) idx_unit(F, 0, U & 3, 63 - (U >> 2));
;         else { const int v = U - 256; idx_unit(F, 1, (v >> 1) & 7, v & 1, v >> 4); }
.LBB0_1258:
	s_cmpk_gt_i32 s15, 0xff
	s_mov_b64 s[10:11], -1
	s_cbranch_scc0 .LBB0_1269
	s_bfe_u32 s10, s15, 0x30001
	s_lshl_b32 s8, s15, 5
	s_lshl_b32 s18, s10, 6
	s_and_b32 s8, s8, 32
	s_or_b32 s8, s18, s8
	s_or_b32 s11, s8, 0x2000
	v_or_b32_e32 v2, s11, v101
	v_lshlrev_b32_e32 v60, 11, v2
	v_or_b32_e32 v4, s11, v100
	v_lshl_add_u64 v[2:3], v[56:57], 0, v[60:61]
	v_lshlrev_b32_e32 v60, 11, v4
	v_or_b32_e32 v10, s11, v99
	v_lshl_add_u64 v[6:7], v[56:57], 0, v[60:61]
	v_lshlrev_b32_e32 v60, 11, v10
	v_or_b32_e32 v12, s11, v98
	v_lshl_add_u64 v[10:11], v[56:57], 0, v[60:61]
	v_lshlrev_b32_e32 v60, 11, v12
	v_or_b32_e32 v18, s11, v97
	v_lshl_add_u64 v[14:15], v[56:57], 0, v[60:61]
	v_lshlrev_b32_e32 v60, 11, v18
	v_or_b32_e32 v20, s11, v96
	v_lshl_add_u64 v[18:19], v[56:57], 0, v[60:61]
	v_lshlrev_b32_e32 v60, 11, v20
	v_or_b32_e32 v26, s11, v95
	v_lshl_add_u64 v[22:23], v[56:57], 0, v[60:61]
	v_lshlrev_b32_e32 v60, 11, v26
	v_or_b32_e32 v28, s11, v94
	v_lshl_add_u64 v[26:27], v[56:57], 0, v[60:61]
	v_lshlrev_b32_e32 v60, 11, v28
	v_lshl_add_u64 v[30:31], v[56:57], 0, v[60:61]
	global_load_dwordx4 v[2:5], v[2:3], off
	s_nop 0
	global_load_dwordx4 v[6:9], v[6:7], off
	s_nop 0
	global_load_dwordx4 v[10:13], v[10:11], off
	s_nop 0
	global_load_dwordx4 v[14:17], v[14:15], off
	s_nop 0
	global_load_dwordx4 v[18:21], v[18:19], off
	s_nop 0
	global_load_dwordx4 v[22:25], v[22:23], off
	s_nop 0
	global_load_dwordx4 v[26:29], v[26:27], off
	s_nop 0
	global_load_dwordx4 v[30:33], v[30:31], off
	v_or_b32_e32 v34, s11, v93
	v_lshlrev_b32_e32 v60, 6, v34
	v_lshl_add_u64 v[34:35], v[62:63], 0, v[60:61]
	global_load_dword v34, v[34:35], off
	s_add_i32 s11, s15, 0xffffff00
	s_lshr_b32 s11, s11, 4
	s_mulk_i32 s11, 0x82
	s_lshr_b32 s17, s11, 2
	s_addk_i32 s11, 0x82
	s_lshr_b32 s16, s11, 2
	v_readlane_b32 s11, v254, 11
	s_add_i32 s17, s17, s11
	s_cmp_ge_u32 s17, s16
	s_waitcnt vmcnt(0)
	ds_write_b128 v53, v[2:5]
	ds_write_b128 v92, v[6:9]
	ds_write_b128 v53, v[10:13] offset:16512
	ds_write_b128 v91, v[14:17]
	ds_write_b128 v53, v[18:21] offset:33024
	ds_write_b128 v90, v[22:25]
	ds_write_b128 v53, v[26:29] offset:49536
	ds_write_b128 v89, v[30:33]
	v_mul_f32_e32 v34, 0x3e000000, v34
	ds_write_b32 v88, v34
	s_waitcnt lgkmcnt(0)
	s_barrier
	s_cbranch_scc1 .LBB0_1268
	s_mulk_i32 s8, 0x4100
	s_bitset1_b32 s18, 12
	s_lshl_b32 s19, s10, 20
	v_lshl_add_u64 v[68:69], v[64:65], 0, s[8:9]

; #define GAS __attribute__((address_space(1)))
; #define LAS __attribute__((address_space(3)))
; __device__ __forceinline__ int crow(int r, int hi) { return (r & 3) + 8 * (r >> 2) + 4 * hi; }
; __device__ __forceinline__ v4u cvt8(const v4u a, const v4u b) { v4u o; o.x = cvtpk(u2f(a.x), u2f(a.y)); o.y = cvtpk(u2f(a.z), u2f(a.w)); o.z = cvtpk(u2f(b.x), u2f(b.y)); o.w = cvtpk(u2f(b.z), u2f(b.w)); return o; }
; __device__ __forceinline__ void idx_unit(Frame& F, int samp, int b, int qb, int part = -1) {
;     ...
;     for (int st = st0 + w; st < st1; st += NWAVES) {
;         const int s = st * 32 + r32; bf16x8 kf[4];
;         if (samp && s < PAST) { const float* kp = F.a->in[6] + ((size_t)b * PAST + s) * 64 + 8 * hi;
; #pragma unroll
;             for (int ks = 0; ks < 4; ++ks) { const v4u a = *(const GAS v4u*)(kp + 16 * ks), c = *(const GAS v4u*)(kp + 16 * ks + 4); kf[ks] = __builtin_bit_cast(bf16x8, cvt8(a, c)); } }
;         else { const bf16* kp = KI + (size_t)(samp ? NP + b * TS + (s - PAST) : b * TP + s) * 64 + 8 * hi;
; #pragma unroll
;             for (int ks = 0; ks < 4; ++ks) kf[ks] = *(const GAS bf16x8*)(kp + 16 * ks); }
;         f32x16 sc;
; #pragma unroll
;         for (int r = 0; r < 16; ++r) sc[r] = 0.f;
; #pragma unroll 2
;         for (int h = 0; h < 16; ++h) {
;             f32x16 acc;
; #pragma unroll
;             for (int r = 0; r < 16; ++r) acc[r] = 0.f;
;             const LAS unsigned char* qp = lds + r32 * QISTR + (h * 64 + 8 * hi) * 2;
; #pragma unroll
;             for (int ks = 0; ks < 4; ++ks) acc = __builtin_amdgcn_mfma_f32_32x32x16_bf16(*(const LAS bf16x8*)(qp + ks * 32), kf[ks], acc, 0, 0, 0);
; #pragma unroll
;             for (int rg = 0; rg < 4; ++rg) { const f32x4 wq = *(const LAS f32x4*)(wiT + h * 32 + 8 * rg + 4 * hi);
; #pragma unroll
;                 for (int e = 0; e < 4; ++e) sc[4 * rg + e] += wq[e] * fmaxf(acc[4 * rg + e] * 0.125f, 0.f); }
;         }
; #pragma unroll
;         for (int r = 0; r < 16; ++r) sc0[(size_t)crow(r, hi) * scld + s] = sc[r];
;     }
.LBB0_1266:
	v_add_u32_e32 v110, s8, v87
	ds_read_b128 v[2:5], v110
	ds_read_b128 v[102:105], v110 offset:32
	ds_read_b128 v[18:21], v110 offset:128
	ds_read_b128 v[106:109], v110 offset:160
	v_add_u32_e32 v114, s8, v59
	v_add_u32_e32 v115, 0x10200, v114
	s_waitcnt vmcnt(3) lgkmcnt(3)
	v_mfma_f32_32x32x16_bf16 v[2:17], v[2:5], v[34:37], 0
	v_add_u32_e32 v116, 0x10220, v114
	v_add_u32_e32 v117, 0x10240, v114
	v_add_u32_e32 v118, 0x10260, v114
	v_add_u32_e32 v122, 0x10280, v114
	v_add_u32_e32 v126, 0x102a0, v114
	v_add_u32_e32 v130, 0x102c0, v114
	v_add_u32_e32 v134, 0x102e0, v114
	s_waitcnt lgkmcnt(1)
	v_mfma_f32_32x32x16_bf16 v[18:33], v[18:21], v[34:37], 0
	s_addk_i32 s8, 0x100
	s_cmpk_eq_i32 s8, 0x800
	s_waitcnt vmcnt(2)
	v_mfma_f32_32x32x16_bf16 v[2:17], v[102:105], v[38:41], v[2:17]
	s_waitcnt lgkmcnt(0)
	v_mfma_f32_32x32x16_bf16 v[18:33], v[106:109], v[38:41], v[18:33]
	ds_read_b128 v[102:105], v110 offset:64
	ds_read_b128 v[106:109], v110 offset:96
	s_waitcnt vmcnt(1) lgkmcnt(1)
	v_mfma_f32_32x32x16_bf16 v[2:17], v[102:105], v[42:45], v[2:17]
	ds_read_b128 v[102:105], v110 offset:192
	ds_read_b128 v[110:113], v110 offset:224
	s_waitcnt lgkmcnt(1)
	v_mfma_f32_32x32x16_bf16 v[18:33], v[102:105], v[42:45], v[18:33]
	ds_read_b128 v[102:105], v115
	s_waitcnt vmcnt(0)
	v_mfma_f32_32x32x16_bf16 v[2:17], v[106:109], v[46:49], v[2:17]
	ds_read_b128 v[106:109], v116
	ds_read_b128 v[114:117], v117
	ds_read_b128 v[118:121], v118
	ds_read_b128 v[122:125], v122
	ds_read_b128 v[126:129], v126
	ds_read_b128 v[130:133], v130
	ds_read_b128 v[134:137], v134
	s_nop 4
	s_waitcnt lgkmcnt(8)
	v_mfma_f32_32x32x16_bf16 v[18:33], v[110:113], v[46:49], v[18:33]
	v_max_f32_e32 v2, 0, v2
	v_max_f32_e32 v3, 0, v3
	v_max_f32_e32 v4, 0, v4
	v_max_f32_e32 v5, 0, v5
	v_max_f32_e32 v6, 0, v6
	v_max_f32_e32 v7, 0, v7
	v_max_f32_e32 v8, 0, v8
	v_max_f32_e32 v9, 0, v9
	v_max_f32_e32 v10, 0, v10
	v_max_f32_e32 v11, 0, v11
	v_max_f32_e32 v12, 0, v12
	v_max_f32_e32 v13, 0, v13
	v_max_f32_e32 v14, 0, v14
	v_max_f32_e32 v15, 0, v15
	v_max_f32_e32 v16, 0, v16
	v_max_f32_e32 v17, 0, v17
	v_max_f32_e32 v18, 0, v18
	v_max_f32_e32 v19, 0, v19
	v_max_f32_e32 v20, 0, v20
	v_max_f32_e32 v21, 0, v21
	v_max_f32_e32 v22, 0, v22
	v_max_f32_e32 v23, 0, v23
	v_max_f32_e32 v24, 0, v24
	v_max_f32_e32 v25, 0, v25
	v_max_f32_e32 v26, 0, v26
	v_max_f32_e32 v27, 0, v27
	v_max_f32_e32 v28, 0, v28
	v_max_f32_e32 v29, 0, v29
	v_max_f32_e32 v30, 0, v30
	v_max_f32_e32 v31, 0, v31
	v_max_f32_e32 v32, 0, v32
	v_max_f32_e32 v33, 0, v33
	s_waitcnt lgkmcnt(7)
	v_pk_fma_f32 v[2:3], v[102:103], v[2:3], v[84:85]
	v_pk_fma_f32 v[4:5], v[104:105], v[4:5], v[82:83]
	s_waitcnt lgkmcnt(6)
	v_pk_fma_f32 v[6:7], v[106:107], v[6:7], v[80:81]
	v_pk_fma_f32 v[8:9], v[108:109], v[8:9], v[78:79]
	s_waitcnt lgkmcnt(5)
	v_pk_fma_f32 v[10:11], v[10:11], v[114:115], v[76:77]
	v_pk_fma_f32 v[12:13], v[12:13], v[116:117], v[74:75]
	s_waitcnt lgkmcnt(4)
	v_pk_fma_f32 v[14:15], v[14:15], v[118:119], v[72:73]
	v_pk_fma_f32 v[16:17], v[16:17], v[120:121], v[70:71]
	s_waitcnt lgkmcnt(3)
	v_pk_fma_f32 v[84:85], v[122:123], v[18:19], v[2:3]
	v_pk_fma_f32 v[82:83], v[124:125], v[20:21], v[4:5]
	s_waitcnt lgkmcnt(2)
	v_pk_fma_f32 v[80:81], v[126:127], v[22:23], v[6:7]
	v_pk_fma_f32 v[78:79], v[128:129], v[24:25], v[8:9]
	s_waitcnt lgkmcnt(1)
	v_pk_fma_f32 v[76:77], v[26:27], v[130:131], v[10:11]
	v_pk_fma_f32 v[74:75], v[28:29], v[132:133], v[12:13]
	s_waitcnt lgkmcnt(0)
	v_pk_fma_f32 v[72:73], v[30:31], v[134:135], v[14:15]
	v_pk_fma_f32 v[70:71], v[32:33], v[136:137], v[16:17]
	s_cbranch_scc0 .LBB0_1266
	v_lshl_add_u64 v[2:3], v[60:61], 2, v[68:69]
	v_add_co_u32_e32 v4, vcc, 0x4000, v2
	global_store_dword v[2:3], v84, off
	s_nop 0
	v_addc_co_u32_e32 v5, vcc, 0, v3, vcc
	global_store_dword v[4:5], v85, off offset:256
	v_add_co_u32_e32 v4, vcc, 0x8000, v2
	s_add_i32 s17, s17, 8
	s_nop 0
	v_addc_co_u32_e32 v5, vcc, 0, v3, vcc
	global_store_dword v[4:5], v82, off offset:512
	v_add_co_u32_e32 v4, vcc, 0xc000, v2
	s_cmp_ge_u32 s17, s16
	s_nop 0
	v_addc_co_u32_e32 v5, vcc, 0, v3, vcc
	global_store_dword v[4:5], v83, off offset:768
	v_add_co_u32_e32 v4, vcc, 0x20000, v2
	s_nop 1
	v_addc_co_u32_e32 v5, vcc, 0, v3, vcc
	global_store_dword v[4:5], v80, off offset:2048
	v_add_co_u32_e32 v4, vcc, 0x24000, v2
	s_nop 1
	v_addc_co_u32_e32 v5, vcc, 0, v3, vcc
	global_store_dword v[4:5], v81, off offset:2304
	v_add_co_u32_e32 v4, vcc, 0x28000, v2
	s_nop 1
	v_addc_co_u32_e32 v5, vcc, 0, v3, vcc
	global_store_dword v[4:5], v78, off offset:2560
	v_add_co_u32_e32 v4, vcc, 0x2c000, v2
	s_nop 1
	v_addc_co_u32_e32 v5, vcc, 0, v3, vcc
	global_store_dword v[4:5], v79, off offset:2816
	v_add_co_u32_e32 v4, vcc, 0x41000, v2
	s_nop 1
	v_addc_co_u32_e32 v5, vcc, 0, v3, vcc
	global_store_dword v[4:5], v76, off
	v_add_co_u32_e32 v4, vcc, 0x45000, v2
	s_nop 1
	v_addc_co_u32_e32 v5, vcc, 0, v3, vcc
	global_store_dword v[4:5], v77, off offset:256
	v_add_co_u32_e32 v4, vcc, 0x49000, v2
	s_nop 1
	v_addc_co_u32_e32 v5, vcc, 0, v3, vcc
	global_store_dword v[4:5], v74, off offset:512
	v_add_co_u32_e32 v4, vcc, 0x4d000, v2
	s_nop 1
	v_addc_co_u32_e32 v5, vcc, 0, v3, vcc
	global_store_dword v[4:5], v75, off offset:768
	v_add_co_u32_e32 v4, vcc, 0x61000, v2
	s_nop 1
	v_addc_co_u32_e32 v5, vcc, 0, v3, vcc
	global_store_dword v[4:5], v72, off offset:2048
	v_add_co_u32_e32 v4, vcc, 0x65000, v2
	s_nop 1
	v_addc_co_u32_e32 v5, vcc, 0, v3, vcc
	global_store_dword v[4:5], v73, off offset:2304
	v_add_co_u32_e32 v4, vcc, 0x69000, v2
	s_nop 1
	v_addc_co_u32_e32 v5, vcc, 0, v3, vcc
	v_add_co_u32_e32 v2, vcc, 0x6d000, v2
	global_store_dword v[4:5], v70, off offset:2560
	s_nop 0
	v_addc_co_u32_e32 v3, vcc, 0, v3, vcc
	global_store_dword v[2:3], v71, off offset:2816
	s_cbranch_scc0 .LBB0_1261

; #define GAS __attribute__((address_space(1)))
; #define LAS __attribute__((address_space(3)))
; __device__ __forceinline__ void idx_unit(Frame& F, int samp, int b, int qb, int part = -1) {
;     ...
;     const int row0 = samp ? NP + b * TS + 32 * qb : b * TP + 32 * qb;
;     const int nadm = samp ? SALL : ((qb >> 1) + 1) * 64, nst = nadm / 32;
;     LAS unsigned char* lds = F.lds; LAS float* wiT = (LAS float*)(lds + 32 * QISTR);
;     const bf16* QI = (const bf16*)(F.ws + WS_QI); const bf16* KI = (const bf16*)(F.ws + WS_KI); const float* WI = (const float*)(F.ws + WS_WI);
;     float* SC = (float*)(F.ws + WS_SC); const int scld = samp ? SALL : 2048; float* sc0 = samp ? SC + SC_S_OFF + (size_t)(row0 - NP) * SALL : SC + (size_t)row0 * 2048;
; #pragma unroll
;     for (int i = 0; i < 8; ++i) { const int p = tid + 512 * i, r = p >> 7, c = p & 127; *(LAS v4u*)(lds + r * QISTR + c * 16) = *(const GAS v4u*)(QI + (size_t)(row0 + r) * 1024 + c * 8); }
;     wiT[(tid & 15) * 32 + (tid >> 4)] = WI[(size_t)(row0 + (tid >> 4)) * 16 + (tid & 15)];
;     __syncthreads();
;     const int st0 = part < 0 ? 0 : (part * nst) >> 2, st1 = part < 0 ? nst : ((part + 1) * nst) >> 2;
;     for (int U = F.bid; U < (F.G == 256 ? 256 : 320); U += F.G) {
;         if (U < 256) idx_unit(F, 0, U & 3, 63 - (U >> 2));
.LBB0_1269:
	s_and_b64 vcc, exec, s[10:11]
	s_cbranch_vccz .LBB0_1257
	s_lshl_b32 s8, s15, 11
	s_and_b32 s10, s8, 0x1800
	s_lshl_b32 s8, s15, 3
	s_andn2_b32 s8, s8, 31
	s_sub_i32 s11, 0x7e0, s8
	s_add_i32 s8, s11, s10
	v_or_b32_e32 v2, s8, v101
	v_or_b32_e32 v4, s8, v100
	v_or_b32_e32 v10, s8, v99
	v_or_b32_e32 v12, s8, v98
	v_or_b32_e32 v18, s8, v97
	v_or_b32_e32 v20, s8, v96
	v_or_b32_e32 v26, s8, v95
	v_or_b32_e32 v28, s8, v94
	v_ashrrev_i32_e32 v3, 31, v2
	v_ashrrev_i32_e32 v5, 31, v4
	v_ashrrev_i32_e32 v11, 31, v10
	v_ashrrev_i32_e32 v13, 31, v12
	v_ashrrev_i32_e32 v19, 31, v18
	v_ashrrev_i32_e32 v21, 31, v20
	v_ashrrev_i32_e32 v27, 31, v26
	v_ashrrev_i32_e32 v29, 31, v28
	v_lshlrev_b64 v[2:3], 11, v[2:3]
	v_lshlrev_b64 v[4:5], 11, v[4:5]
	v_lshlrev_b64 v[10:11], 11, v[10:11]
	v_lshlrev_b64 v[12:13], 11, v[12:13]
	v_lshlrev_b64 v[18:19], 11, v[18:19]
	v_lshlrev_b64 v[20:21], 11, v[20:21]
	v_lshlrev_b64 v[26:27], 11, v[26:27]
	v_lshlrev_b64 v[28:29], 11, v[28:29]
	v_lshl_add_u64 v[2:3], v[56:57], 0, v[2:3]
	v_lshl_add_u64 v[6:7], v[56:57], 0, v[4:5]
	v_lshl_add_u64 v[10:11], v[56:57], 0, v[10:11]
	v_lshl_add_u64 v[14:15], v[56:57], 0, v[12:13]
	v_lshl_add_u64 v[18:19], v[56:57], 0, v[18:19]
	v_lshl_add_u64 v[22:23], v[56:57], 0, v[20:21]
	v_lshl_add_u64 v[26:27], v[56:57], 0, v[26:27]
	v_lshl_add_u64 v[30:31], v[56:57], 0, v[28:29]
	global_load_dwordx4 v[2:5], v[2:3], off
	s_nop 0
	global_load_dwordx4 v[6:9], v[6:7], off
	s_nop 0
	global_load_dwordx4 v[10:13], v[10:11], off
	s_nop 0
	global_load_dwordx4 v[14:17], v[14:15], off
	s_nop 0
	global_load_dwordx4 v[18:21], v[18:19], off
	s_nop 0
	global_load_dwordx4 v[22:25], v[22:23], off
	s_nop 0
	global_load_dwordx4 v[26:29], v[26:27], off
	s_nop 0
	global_load_dwordx4 v[30:33], v[30:31], off
	v_or_b32_e32 v34, s8, v93
	v_ashrrev_i32_e32 v35, 31, v34
	v_lshlrev_b64 v[34:35], 6, v[34:35]
	v_lshl_add_u64 v[34:35], v[62:63], 0, v[34:35]
	global_load_dword v34, v[34:35], off
	s_andn2_b32 s11, s11, 63
	s_add_i32 s11, s11, 64
	s_lshr_b32 s11, s11, 5
	v_readlane_b32 s16, v254, 11
	s_cmp_ge_u32 s16, s11
	s_waitcnt vmcnt(0)
	ds_write_b128 v53, v[2:5]
	ds_write_b128 v92, v[6:9]
	ds_write_b128 v53, v[10:13] offset:16512
	ds_write_b128 v91, v[14:17]
	ds_write_b128 v53, v[18:21] offset:33024
	ds_write_b128 v90, v[22:25]
	ds_write_b128 v53, v[26:29] offset:49536
	ds_write_b128 v89, v[30:33]
	v_mul_f32_e32 v34, 0x3e000000, v34
	ds_write_b32 v88, v34
	s_waitcnt lgkmcnt(0)
	s_barrier
	s_cbranch_scc1 .LBB0_1256
	s_lshl_b64 s[16:17], s[8:9], 13
	v_lshl_add_u64 v[68:69], v[66:67], 0, s[16:17]
	v_readlane_b32 s8, v254, 11

; #define GAS __attribute__((address_space(1)))
; #define LAS __attribute__((address_space(3)))
; __device__ __forceinline__ int crow(int r, int hi) { return (r & 3) + 8 * (r >> 2) + 4 * hi; }
; __device__ __forceinline__ v4u cvt8(const v4u a, const v4u b) { v4u o; o.x = cvtpk(u2f(a.x), u2f(a.y)); o.y = cvtpk(u2f(a.z), u2f(a.w)); o.z = cvtpk(u2f(b.x), u2f(b.y)); o.w = cvtpk(u2f(b.z), u2f(b.w)); return o; }
; __device__ __forceinline__ void idx_unit(Frame& F, int samp, int b, int qb, int part = -1) {
;     ...
;     for (int st = st0 + w; st < st1; st += NWAVES) {
;         const int s = st * 32 + r32; bf16x8 kf[4];
;         if (samp && s < PAST) { const float* kp = F.a->in[6] + ((size_t)b * PAST + s) * 64 + 8 * hi;
; #pragma unroll
;             for (int ks = 0; ks < 4; ++ks) { const v4u a = *(const GAS v4u*)(kp + 16 * ks), c = *(const GAS v4u*)(kp + 16 * ks + 4); kf[ks] = __builtin_bit_cast(bf16x8, cvt8(a, c)); } }
;         else { const bf16* kp = KI + (size_t)(samp ? NP + b * TS + (s - PAST) : b * TP + s) * 64 + 8 * hi;
; #pragma unroll
;             for (int ks = 0; ks < 4; ++ks) kf[ks] = *(const GAS bf16x8*)(kp + 16 * ks); }
;         f32x16 sc;
; #pragma unroll
;         for (int r = 0; r < 16; ++r) sc[r] = 0.f;
; #pragma unroll 2
;         for (int h = 0; h < 16; ++h) {
;             f32x16 acc;
; #pragma unroll
;             for (int r = 0; r < 16; ++r) acc[r] = 0.f;
;             const LAS unsigned char* qp = lds + r32 * QISTR + (h * 64 + 8 * hi) * 2;
; #pragma unroll
;             for (int ks = 0; ks < 4; ++ks) acc = __builtin_amdgcn_mfma_f32_32x32x16_bf16(*(const LAS bf16x8*)(qp + ks * 32), kf[ks], acc, 0, 0, 0);
; #pragma unroll
;             for (int rg = 0; rg < 4; ++rg) { const f32x4 wq = *(const LAS f32x4*)(wiT + h * 32 + 8 * rg + 4 * hi);
; #pragma unroll
;                 for (int e = 0; e < 4; ++e) sc[4 * rg + e] += wq[e] * fmaxf(acc[4 * rg + e] * 0.125f, 0.f); }
;         }
; #pragma unroll
;         for (int r = 0; r < 16; ++r) sc0[(size_t)crow(r, hi) * scld + s] = sc[r];
;     }
.LBB0_1273:
	v_add_u32_e32 v110, s16, v87
	ds_read_b128 v[2:5], v110
	ds_read_b128 v[102:105], v110 offset:32
	ds_read_b128 v[18:21], v110 offset:128
	ds_read_b128 v[106:109], v110 offset:160
	v_add_u32_e32 v114, s16, v59
	v_add_u32_e32 v115, 0x10200, v114
	s_waitcnt vmcnt(3) lgkmcnt(3)
	v_mfma_f32_32x32x16_bf16 v[2:17], v[2:5], v[34:37], 0
	v_add_u32_e32 v116, 0x10220, v114
	v_add_u32_e32 v117, 0x10240, v114
	v_add_u32_e32 v118, 0x10260, v114
	v_add_u32_e32 v122, 0x10280, v114
	v_add_u32_e32 v126, 0x102a0, v114
	v_add_u32_e32 v130, 0x102c0, v114
	v_add_u32_e32 v134, 0x102e0, v114
	s_waitcnt lgkmcnt(1)
	v_mfma_f32_32x32x16_bf16 v[18:33], v[18:21], v[34:37], 0
	s_addk_i32 s16, 0x100
	s_cmpk_eq_i32 s16, 0x800
	s_waitcnt vmcnt(2)
	v_mfma_f32_32x32x16_bf16 v[2:17], v[102:105], v[38:41], v[2:17]
	s_waitcnt lgkmcnt(0)
	v_mfma_f32_32x32x16_bf16 v[18:33], v[106:109], v[38:41], v[18:33]
	ds_read_b128 v[102:105], v110 offset:64
	ds_read_b128 v[106:109], v110 offset:96
	s_waitcnt vmcnt(1) lgkmcnt(1)
	v_mfma_f32_32x32x16_bf16 v[2:17], v[102:105], v[42:45], v[2:17]
	ds_read_b128 v[102:105], v110 offset:192
	ds_read_b128 v[110:113], v110 offset:224
	s_waitcnt lgkmcnt(1)
	v_mfma_f32_32x32x16_bf16 v[18:33], v[102:105], v[42:45], v[18:33]
	ds_read_b128 v[102:105], v115
	s_waitcnt vmcnt(0)
	v_mfma_f32_32x32x16_bf16 v[2:17], v[106:109], v[46:49], v[2:17]
	ds_read_b128 v[106:109], v116
	ds_read_b128 v[114:117], v117
	ds_read_b128 v[118:121], v118
	ds_read_b128 v[122:125], v122
	ds_read_b128 v[126:129], v126
	ds_read_b128 v[130:133], v130
	ds_read_b128 v[134:137], v134
	s_nop 4
	s_waitcnt lgkmcnt(8)
	v_mfma_f32_32x32x16_bf16 v[18:33], v[110:113], v[46:49], v[18:33]
	v_max_f32_e32 v2, 0, v2
	v_max_f32_e32 v3, 0, v3
	v_max_f32_e32 v4, 0, v4
	v_max_f32_e32 v5, 0, v5
	v_max_f32_e32 v6, 0, v6
	v_max_f32_e32 v7, 0, v7
	v_max_f32_e32 v8, 0, v8
	v_max_f32_e32 v9, 0, v9
	v_max_f32_e32 v10, 0, v10
	v_max_f32_e32 v11, 0, v11
	v_max_f32_e32 v12, 0, v12
	v_max_f32_e32 v13, 0, v13
	v_max_f32_e32 v14, 0, v14
	v_max_f32_e32 v15, 0, v15
	v_max_f32_e32 v16, 0, v16
	v_max_f32_e32 v17, 0, v17
	v_max_f32_e32 v18, 0, v18
	v_max_f32_e32 v19, 0, v19
	v_max_f32_e32 v20, 0, v20
	v_max_f32_e32 v21, 0, v21
	v_max_f32_e32 v22, 0, v22
	v_max_f32_e32 v23, 0, v23
	v_max_f32_e32 v24, 0, v24
	v_max_f32_e32 v25, 0, v25
	v_max_f32_e32 v26, 0, v26
	v_max_f32_e32 v27, 0, v27
	v_max_f32_e32 v28, 0, v28
	v_max_f32_e32 v29, 0, v29
	v_max_f32_e32 v30, 0, v30
	v_max_f32_e32 v31, 0, v31
	v_max_f32_e32 v32, 0, v32
	v_max_f32_e32 v33, 0, v33
	s_waitcnt lgkmcnt(7)
	v_pk_fma_f32 v[2:3], v[102:103], v[2:3], v[84:85]
	v_pk_fma_f32 v[4:5], v[104:105], v[4:5], v[82:83]
	s_waitcnt lgkmcnt(6)
	v_pk_fma_f32 v[6:7], v[106:107], v[6:7], v[80:81]
	v_pk_fma_f32 v[8:9], v[108:109], v[8:9], v[78:79]
	s_waitcnt lgkmcnt(5)
	v_pk_fma_f32 v[10:11], v[10:11], v[114:115], v[76:77]
	v_pk_fma_f32 v[12:13], v[12:13], v[116:117], v[74:75]
	s_waitcnt lgkmcnt(4)
	v_pk_fma_f32 v[14:15], v[14:15], v[118:119], v[72:73]
	v_pk_fma_f32 v[16:17], v[16:17], v[120:121], v[70:71]
	s_waitcnt lgkmcnt(3)
	v_pk_fma_f32 v[84:85], v[122:123], v[18:19], v[2:3]
	v_pk_fma_f32 v[82:83], v[124:125], v[20:21], v[4:5]
	s_waitcnt lgkmcnt(2)
	v_pk_fma_f32 v[80:81], v[126:127], v[22:23], v[6:7]
	v_pk_fma_f32 v[78:79], v[128:129], v[24:25], v[8:9]
	s_waitcnt lgkmcnt(1)
	v_pk_fma_f32 v[76:77], v[26:27], v[130:131], v[10:11]
	v_pk_fma_f32 v[74:75], v[28:29], v[132:133], v[12:13]
	s_waitcnt lgkmcnt(0)
	v_pk_fma_f32 v[72:73], v[30:31], v[134:135], v[14:15]
	v_pk_fma_f32 v[70:71], v[32:33], v[136:137], v[16:17]
	s_cbranch_scc0 .LBB0_1273
	v_lshl_add_u64 v[2:3], v[60:61], 2, v[68:69]
	v_add_co_u32_e32 v4, vcc, 0x2000, v2
	global_store_dword v[2:3], v84, off
	s_nop 0
	v_addc_co_u32_e32 v5, vcc, 0, v3, vcc
	global_store_dword v[4:5], v85, off
	v_add_co_u32_e32 v4, vcc, 0x4000, v2
	s_add_i32 s8, s8, 8
	s_nop 0
	v_addc_co_u32_e32 v5, vcc, 0, v3, vcc
	global_store_dword v[4:5], v82, off
	v_add_co_u32_e32 v4, vcc, 0x6000, v2
	s_cmp_ge_u32 s8, s11
	s_nop 0
	v_addc_co_u32_e32 v5, vcc, 0, v3, vcc
	global_store_dword v[4:5], v83, off
	v_add_co_u32_e32 v4, vcc, 0x10000, v2
	s_nop 1
	v_addc_co_u32_e32 v5, vcc, 0, v3, vcc
	global_store_dword v[4:5], v80, off
	v_add_co_u32_e32 v4, vcc, 0x12000, v2
	s_nop 1
	v_addc_co_u32_e32 v5, vcc, 0, v3, vcc
	global_store_dword v[4:5], v81, off
	v_add_co_u32_e32 v4, vcc, 0x14000, v2
	s_nop 1
	v_addc_co_u32_e32 v5, vcc, 0, v3, vcc
	global_store_dword v[4:5], v78, off
	v_add_co_u32_e32 v4, vcc, 0x16000, v2
	s_nop 1
	v_addc_co_u32_e32 v5, vcc, 0, v3, vcc
	global_store_dword v[4:5], v79, off
	v_add_co_u32_e32 v4, vcc, s13, v2
	s_nop 1
	v_addc_co_u32_e32 v5, vcc, 0, v3, vcc
	global_store_dword v[4:5], v76, off
	v_add_co_u32_e32 v4, vcc, 0x22000, v2
	s_nop 1
	v_addc_co_u32_e32 v5, vcc, 0, v3, vcc
	global_store_dword v[4:5], v77, off
	v_add_co_u32_e32 v4, vcc, s14, v2
	s_nop 1
	v_addc_co_u32_e32 v5, vcc, 0, v3, vcc
	global_store_dword v[4:5], v74, off
	v_add_co_u32_e32 v4, vcc, 0x26000, v2
	s_nop 1
	v_addc_co_u32_e32 v5, vcc, 0, v3, vcc
	global_store_dword v[4:5], v75, off
	v_add_co_u32_e32 v4, vcc, 0x30000, v2
	s_nop 1
	v_addc_co_u32_e32 v5, vcc, 0, v3, vcc
	global_store_dword v[4:5], v72, off
	v_add_co_u32_e32 v4, vcc, 0x32000, v2
	s_nop 1
	v_addc_co_u32_e32 v5, vcc, 0, v3, vcc
	global_store_dword v[4:5], v73, off
	v_add_co_u32_e32 v4, vcc, 0x34000, v2
	s_nop 1
	v_addc_co_u32_e32 v5, vcc, 0, v3, vcc
	v_add_co_u32_e32 v2, vcc, 0x36000, v2
	global_store_dword v[4:5], v70, off
	s_nop 0
	v_addc_co_u32_e32 v3, vcc, 0, v3, vcc
	global_store_dword v[2:3], v71, off
	s_cbranch_scc0 .LBB0_1272
	s_branch .LBB0_1256
; #define GAS __attribute__((address_space(1)))
; #define LAS __attribute__((address_space(3)))
; __device__ __forceinline__ void idx_unit(Frame& F, int samp, int b, int qb, int part = -1) {
;     ...
;     const int row0 = samp ? NP + b * TS + 32 * qb : b * TP + 32 * qb;
;     const int nadm = samp ? SALL : ((qb >> 1) + 1) * 64, nst = nadm / 32;
;     LAS unsigned char* lds = F.lds; LAS float* wiT = (LAS float*)(lds + 32 * QISTR);
;     const bf16* QI = (const bf16*)(F.ws + WS_QI); const bf16* KI = (const bf16*)(F.ws + WS_KI); const float* WI = (const float*)(F.ws + WS_WI);
;     float* SC = (float*)(F.ws + WS_SC); const int scld = samp ? SALL : 2048; float* sc0 = samp ? SC + SC_S_OFF + (size_t)(row0 - NP) * SALL : SC + (size_t)row0 * 2048;
; #pragma unroll
;     for (int i = 0; i < 8; ++i) { const int p = tid + 512 * i, r = p >> 7, c = p & 127; *(LAS v4u*)(lds + r * QISTR + c * 16) = *(const GAS v4u*)(QI + (size_t)(row0 + r) * 1024 + c * 8); }
;     wiT[(tid & 15) * 32 + (tid >> 4)] = WI[(size_t)(row0 + (tid >> 4)) * 16 + (tid & 15)];
;     __syncthreads();
;     const int st0 = part < 0 ? 0 : (part * nst) >> 2, st1 = part < 0 ? nst : ((part + 1) * nst) >> 2;
;     ...
;     if (F.G == 256 && F.bid >= 192) { const int v = 255 - F.bid; idx_unit(F, 1, (v >> 1) & 7, v & 1, v >> 4); }
.LBB0_1275:
	s_cmpk_gt_i32 s83, 0xbf
	s_cselect_b64 s[8:9], -1, 0
	s_and_b64 s[6:7], s[8:9], s[6:7]
	s_and_b64 vcc, exec, s[6:7]
	s_cbranch_vccz .LBB0_1286
	s_sub_i32 s9, 0xff, s83
	s_bfe_u32 s7, s9, 0x30001
	s_lshl_b32 s8, s9, 5
	s_lshl_b32 s6, s7, 6
	s_and_b32 s8, s8, 32
	s_or_b32 s8, s6, s8
	s_or_b32 s10, s8, 0x2000
	v_or_b32_e32 v2, s10, v101
	v_lshlrev_b32_e32 v60, 11, v2
	v_mov_b32_e32 v61, 0
	v_or_b32_e32 v2, s10, v100
	v_lshl_add_u64 v[34:35], v[56:57], 0, v[60:61]
	v_lshlrev_b32_e32 v60, 11, v2
	v_or_b32_e32 v2, s10, v99
	v_lshl_add_u64 v[36:37], v[56:57], 0, v[60:61]
	v_lshlrev_b32_e32 v60, 11, v2
	v_or_b32_e32 v2, s10, v98
	v_lshl_add_u64 v[38:39], v[56:57], 0, v[60:61]
	v_lshlrev_b32_e32 v60, 11, v2
	v_or_b32_e32 v2, s10, v97
	v_lshl_add_u64 v[40:41], v[56:57], 0, v[60:61]
	v_lshlrev_b32_e32 v60, 11, v2
	v_or_b32_e32 v2, s10, v96
	v_lshl_add_u64 v[42:43], v[56:57], 0, v[60:61]
	v_lshlrev_b32_e32 v60, 11, v2
	v_or_b32_e32 v2, s10, v95
	v_lshl_add_u64 v[44:45], v[56:57], 0, v[60:61]
	v_lshlrev_b32_e32 v60, 11, v2
	v_or_b32_e32 v2, s10, v94
	v_lshl_add_u64 v[46:47], v[56:57], 0, v[60:61]
	v_lshlrev_b32_e32 v60, 11, v2
	v_or_b32_e32 v2, s10, v93
	v_lshl_add_u64 v[48:49], v[56:57], 0, v[60:61]
	v_lshlrev_b32_e32 v60, 6, v2
	v_lshl_add_u64 v[2:3], s[4:5], 0, v[60:61]
	v_mov_b32_e32 v59, v61
	v_lshl_add_u64 v[56:57], v[2:3], 0, v[58:59]
	global_load_dwordx4 v[2:5], v[34:35], off
	global_load_dwordx4 v[6:9], v[36:37], off
	global_load_dwordx4 v[10:13], v[38:39], off
	global_load_dwordx4 v[14:17], v[40:41], off
	global_load_dwordx4 v[18:21], v[42:43], off
	global_load_dwordx4 v[22:25], v[44:45], off
	global_load_dwordx4 v[26:29], v[46:47], off
	global_load_dwordx4 v[30:33], v[48:49], off
	global_load_dword v58, v[56:57], off
	s_ashr_i32 s4, s9, 4
	s_mul_i32 s5, s4, 0x82
	s_lshr_b32 s9, s5, 2
	s_addk_i32 s5, 0x82
	s_lshr_b32 s5, s5, 2
	s_cmp_lt_i32 s4, 0
	s_cselect_b32 s9, 0, s9
	s_cselect_b32 s4, 0x82, s5
	v_readlane_b32 s5, v254, 11
	s_add_i32 s5, s5, s9
	s_cmp_ge_u32 s5, s4
	s_waitcnt vmcnt(0)
	ds_write_b128 v53, v[2:5]
	ds_write_b128 v92, v[6:9]
	ds_write_b128 v53, v[10:13] offset:16512
	ds_write_b128 v91, v[14:17]
	ds_write_b128 v53, v[18:21] offset:33024
	ds_write_b128 v90, v[22:25]
	ds_write_b128 v53, v[26:29] offset:49536
	ds_write_b128 v89, v[30:33]
	v_mul_f32_e32 v58, 0x3e000000, v58
	ds_write_b32 v88, v58
	s_waitcnt lgkmcnt(0)
	s_barrier
	s_cbranch_scc1 .LBB0_1285
	s_mulk_i32 s8, 0x4100
	s_add_u32 s2, s2, s8
	s_addc_u32 s3, s3, 0
	s_bitset1_b32 s6, 12
	s_lshl_b32 s7, s7, 20
	v_lshl_add_u64 v[54:55], s[2:3], 0, v[54:55]
	v_add_u32_e32 v72, 0, v52

; #define GAS __attribute__((address_space(1)))
; #define LAS __attribute__((address_space(3)))
; __device__ __forceinline__ int crow(int r, int hi) { return (r & 3) + 8 * (r >> 2) + 4 * hi; }
; __device__ __forceinline__ v4u cvt8(const v4u a, const v4u b) { v4u o; o.x = cvtpk(u2f(a.x), u2f(a.y)); o.y = cvtpk(u2f(a.z), u2f(a.w)); o.z = cvtpk(u2f(b.x), u2f(b.y)); o.w = cvtpk(u2f(b.z), u2f(b.w)); return o; }
; __device__ __forceinline__ void idx_unit(Frame& F, int samp, int b, int qb, int part = -1) {
;     ...
;     for (int st = st0 + w; st < st1; st += NWAVES) {
;         const int s = st * 32 + r32; bf16x8 kf[4];
;         if (samp && s < PAST) { const float* kp = F.a->in[6] + ((size_t)b * PAST + s) * 64 + 8 * hi;
; #pragma unroll
;             for (int ks = 0; ks < 4; ++ks) { const v4u a = *(const GAS v4u*)(kp + 16 * ks), c = *(const GAS v4u*)(kp + 16 * ks + 4); kf[ks] = __builtin_bit_cast(bf16x8, cvt8(a, c)); } }
;         else { const bf16* kp = KI + (size_t)(samp ? NP + b * TS + (s - PAST) : b * TP + s) * 64 + 8 * hi;
; #pragma unroll
;             for (int ks = 0; ks < 4; ++ks) kf[ks] = *(const GAS bf16x8*)(kp + 16 * ks); }
;         f32x16 sc;
; #pragma unroll
;         for (int r = 0; r < 16; ++r) sc[r] = 0.f;
; #pragma unroll 2
;         for (int h = 0; h < 16; ++h) {
;             f32x16 acc;
; #pragma unroll
;             for (int r = 0; r < 16; ++r) acc[r] = 0.f;
;             const LAS unsigned char* qp = lds + r32 * QISTR + (h * 64 + 8 * hi) * 2;
; #pragma unroll
;             for (int ks = 0; ks < 4; ++ks) acc = __builtin_amdgcn_mfma_f32_32x32x16_bf16(*(const LAS bf16x8*)(qp + ks * 32), kf[ks], acc, 0, 0, 0);
; #pragma unroll
;             for (int rg = 0; rg < 4; ++rg) { const f32x4 wq = *(const LAS f32x4*)(wiT + h * 32 + 8 * rg + 4 * hi);
; #pragma unroll
;                 for (int e = 0; e < 4; ++e) sc[4 * rg + e] += wq[e] * fmaxf(acc[4 * rg + e] * 0.125f, 0.f); }
;         }
; #pragma unroll
;         for (int r = 0; r < 16; ++r) sc0[(size_t)crow(r, hi) * scld + s] = sc[r];
;     }
.LBB0_1283:
	v_add_u32_e32 v73, s2, v87
	ds_read_b128 v[2:5], v73
	ds_read_b128 v[74:77], v73 offset:32
	ds_read_b128 v[18:21], v73 offset:128
	ds_read_b128 v[78:81], v73 offset:160
	v_add_u32_e32 v88, s2, v72
	v_add_u32_e32 v89, 0x10200, v88
	s_waitcnt vmcnt(3) lgkmcnt(3)
	v_mfma_f32_32x32x16_bf16 v[2:17], v[2:5], v[34:37], 0
	v_add_u32_e32 v90, 0x10220, v88
	v_add_u32_e32 v91, 0x10240, v88
	v_add_u32_e32 v96, 0x10280, v88
	v_add_u32_e32 v100, 0x102a0, v88
	v_add_u32_e32 v104, 0x102c0, v88
	v_add_u32_e32 v108, 0x102e0, v88
	s_addk_i32 s2, 0x100
	s_waitcnt lgkmcnt(1)
	v_mfma_f32_32x32x16_bf16 v[18:33], v[18:21], v[34:37], 0
	s_cmpk_eq_i32 s2, 0x800
	s_waitcnt vmcnt(2)
	v_mfma_f32_32x32x16_bf16 v[2:17], v[74:77], v[38:41], v[2:17]
	s_waitcnt lgkmcnt(0)
	v_mfma_f32_32x32x16_bf16 v[18:33], v[78:81], v[38:41], v[18:33]
	ds_read_b128 v[74:77], v73 offset:64
	ds_read_b128 v[78:81], v73 offset:96
	ds_read_b128 v[82:85], v73 offset:224
	s_waitcnt vmcnt(1) lgkmcnt(2)
	v_mfma_f32_32x32x16_bf16 v[2:17], v[74:77], v[42:45], v[2:17]
	ds_read_b128 v[74:77], v73 offset:192
	v_add_u32_e32 v73, 0x10260, v88
	s_waitcnt lgkmcnt(0)
	v_mfma_f32_32x32x16_bf16 v[18:33], v[74:77], v[42:45], v[18:33]
	ds_read_b128 v[74:77], v89
	s_waitcnt vmcnt(0)
	v_mfma_f32_32x32x16_bf16 v[2:17], v[78:81], v[46:49], v[2:17]
	ds_read_b128 v[78:81], v90
	ds_read_b128 v[88:91], v91
	ds_read_b128 v[92:95], v73
	ds_read_b128 v[96:99], v96
	ds_read_b128 v[100:103], v100
	ds_read_b128 v[104:107], v104
	ds_read_b128 v[108:111], v108
	s_nop 4
	v_mfma_f32_32x32x16_bf16 v[18:33], v[82:85], v[46:49], v[18:33]
	v_max_f32_e32 v2, 0, v2
	v_max_f32_e32 v3, 0, v3
	v_max_f32_e32 v4, 0, v4
	v_max_f32_e32 v5, 0, v5
	v_max_f32_e32 v6, 0, v6
	v_max_f32_e32 v7, 0, v7
	v_max_f32_e32 v8, 0, v8
	v_max_f32_e32 v9, 0, v9
	v_max_f32_e32 v10, 0, v10
	v_max_f32_e32 v11, 0, v11
	v_max_f32_e32 v12, 0, v12
	v_max_f32_e32 v13, 0, v13
	v_max_f32_e32 v14, 0, v14
	v_max_f32_e32 v15, 0, v15
	v_max_f32_e32 v16, 0, v16
	v_max_f32_e32 v17, 0, v17
	v_max_f32_e32 v18, 0, v18
	v_max_f32_e32 v19, 0, v19
	v_max_f32_e32 v20, 0, v20
	v_max_f32_e32 v21, 0, v21
	v_max_f32_e32 v22, 0, v22
	v_max_f32_e32 v23, 0, v23
	v_max_f32_e32 v24, 0, v24
	v_max_f32_e32 v25, 0, v25
	v_max_f32_e32 v26, 0, v26
	v_max_f32_e32 v27, 0, v27
	v_max_f32_e32 v28, 0, v28
	v_max_f32_e32 v29, 0, v29
	v_max_f32_e32 v30, 0, v30
	v_max_f32_e32 v31, 0, v31
	v_max_f32_e32 v32, 0, v32
	v_max_f32_e32 v33, 0, v33
	s_waitcnt lgkmcnt(7)
	v_pk_fma_f32 v[2:3], v[74:75], v[2:3], v[70:71]
	v_pk_fma_f32 v[4:5], v[76:77], v[4:5], v[68:69]
	s_waitcnt lgkmcnt(6)
	v_pk_fma_f32 v[6:7], v[78:79], v[6:7], v[66:67]
	v_pk_fma_f32 v[8:9], v[80:81], v[8:9], v[64:65]
	s_waitcnt lgkmcnt(5)
	v_pk_fma_f32 v[10:11], v[10:11], v[88:89], v[62:63]
	v_pk_fma_f32 v[12:13], v[12:13], v[90:91], v[58:59]
	s_waitcnt lgkmcnt(4)
	v_pk_fma_f32 v[14:15], v[14:15], v[92:93], v[56:57]
	v_pk_fma_f32 v[16:17], v[16:17], v[94:95], v[52:53]
	s_waitcnt lgkmcnt(3)
	v_pk_fma_f32 v[70:71], v[96:97], v[18:19], v[2:3]
	v_pk_fma_f32 v[68:69], v[98:99], v[20:21], v[4:5]
	s_waitcnt lgkmcnt(2)
	v_pk_fma_f32 v[66:67], v[100:101], v[22:23], v[6:7]
	v_pk_fma_f32 v[64:65], v[102:103], v[24:25], v[8:9]
	s_waitcnt lgkmcnt(1)
	v_pk_fma_f32 v[62:63], v[26:27], v[104:105], v[10:11]
	v_pk_fma_f32 v[58:59], v[28:29], v[106:107], v[12:13]
	s_waitcnt lgkmcnt(0)
	v_pk_fma_f32 v[56:57], v[30:31], v[108:109], v[14:15]
	v_pk_fma_f32 v[52:53], v[32:33], v[110:111], v[16:17]
	s_cbranch_scc0 .LBB0_1283
	v_lshl_add_u64 v[2:3], v[60:61], 2, v[54:55]
	v_add_co_u32_e32 v4, vcc, 0x4000, v2
	global_store_dword v[2:3], v70, off
	s_nop 0
	v_addc_co_u32_e32 v5, vcc, 0, v3, vcc
	global_store_dword v[4:5], v71, off offset:256
	v_add_co_u32_e32 v4, vcc, 0x8000, v2
	s_add_i32 s5, s5, 8
	s_nop 0
	v_addc_co_u32_e32 v5, vcc, 0, v3, vcc
	global_store_dword v[4:5], v68, off offset:512
	v_add_co_u32_e32 v4, vcc, 0xc000, v2
	s_cmp_ge_u32 s5, s4
	s_nop 0
	v_addc_co_u32_e32 v5, vcc, 0, v3, vcc
	global_store_dword v[4:5], v69, off offset:768
	v_add_co_u32_e32 v4, vcc, 0x20000, v2
	s_nop 1
	v_addc_co_u32_e32 v5, vcc, 0, v3, vcc
	global_store_dword v[4:5], v66, off offset:2048
	v_add_co_u32_e32 v4, vcc, 0x24000, v2
	s_nop 1
	v_addc_co_u32_e32 v5, vcc, 0, v3, vcc
	global_store_dword v[4:5], v67, off offset:2304
	v_add_co_u32_e32 v4, vcc, 0x28000, v2
	s_nop 1
	v_addc_co_u32_e32 v5, vcc, 0, v3, vcc
	global_store_dword v[4:5], v64, off offset:2560
	v_add_co_u32_e32 v4, vcc, 0x2c000, v2
	s_nop 1
	v_addc_co_u32_e32 v5, vcc, 0, v3, vcc
	global_store_dword v[4:5], v65, off offset:2816
	v_add_co_u32_e32 v4, vcc, 0x41000, v2
	s_nop 1
	v_addc_co_u32_e32 v5, vcc, 0, v3, vcc
	global_store_dword v[4:5], v62, off
	v_add_co_u32_e32 v4, vcc, 0x45000, v2
	s_nop 1
	v_addc_co_u32_e32 v5, vcc, 0, v3, vcc
	global_store_dword v[4:5], v63, off offset:256
	v_add_co_u32_e32 v4, vcc, 0x49000, v2
	s_nop 1
	v_addc_co_u32_e32 v5, vcc, 0, v3, vcc
	global_store_dword v[4:5], v58, off offset:512
	v_add_co_u32_e32 v4, vcc, 0x4d000, v2
	s_nop 1
	v_addc_co_u32_e32 v5, vcc, 0, v3, vcc
	global_store_dword v[4:5], v59, off offset:768
	v_add_co_u32_e32 v4, vcc, 0x61000, v2
	s_nop 1
	v_addc_co_u32_e32 v5, vcc, 0, v3, vcc
	global_store_dword v[4:5], v56, off offset:2048
	v_add_co_u32_e32 v4, vcc, 0x65000, v2
	s_nop 1
	v_addc_co_u32_e32 v5, vcc, 0, v3, vcc
	global_store_dword v[4:5], v57, off offset:2304
	v_add_co_u32_e32 v4, vcc, 0x69000, v2
	s_nop 1
	v_addc_co_u32_e32 v5, vcc, 0, v3, vcc
	v_add_co_u32_e32 v2, vcc, 0x6d000, v2
	global_store_dword v[4:5], v52, off offset:2560
	s_nop 0
	v_addc_co_u32_e32 v3, vcc, 0, v3, vcc
	global_store_dword v[2:3], v53, off offset:2816
	s_cbranch_scc0 .LBB0_1278
